# Final: same instructions as v36, metadata sgpr_count made consistent with next_free_sgpr 102
# speedup vs baseline: 1.0077x; 1.0077x over previous
; __global__ void __launch_bounds__(512, 2) hybrid_fwd(Args a) {
;     extern __shared__ __attribute__((aligned(16))) unsigned char lds_raw[];
amdhsa.kernels:
  - .agpr_count:     0
    .args:
      - .offset:         0
        .size:           136
        .value_kind:     by_value
      - .offset:         136
        .size:           4
        .value_kind:     hidden_block_count_x
      - .offset:         140
        .size:           4
        .value_kind:     hidden_block_count_y
      - .offset:         144
        .size:           4
        .value_kind:     hidden_block_count_z
      - .offset:         148
        .size:           2
        .value_kind:     hidden_group_size_x
      - .offset:         150
        .size:           2
        .value_kind:     hidden_group_size_y
      - .offset:         152
        .size:           2
        .value_kind:     hidden_group_size_z
      - .offset:         154
        .size:           2
        .value_kind:     hidden_remainder_x
      - .offset:         156
        .size:           2
        .value_kind:     hidden_remainder_y
      - .offset:         158
        .size:           2
        .value_kind:     hidden_remainder_z
      - .offset:         176
        .size:           8
        .value_kind:     hidden_global_offset_x
      - .offset:         184
        .size:           8
        .value_kind:     hidden_global_offset_y
      - .offset:         192
        .size:           8
        .value_kind:     hidden_global_offset_z
      - .offset:         200
        .size:           2
        .value_kind:     hidden_grid_dims
      - .offset:         224
        .size:           8
        .value_kind:     hidden_multigrid_sync_arg
      - .offset:         256
        .size:           4
        .value_kind:     hidden_dynamic_lds_size
    .group_segment_fixed_size: 0
    .kernarg_segment_align: 8
    .kernarg_segment_size: 392
    .language:       OpenCL C
    .language_version:
      - 2
      - 0
    .max_flat_workgroup_size: 512
    .name:           _Z10hybrid_fwd4Args
    .private_segment_fixed_size: 0
    .sgpr_count:     108
    .sgpr_spill_count: 149
    .symbol:         _Z10hybrid_fwd4Args.kd
    .uniform_work_group_size: 1
    .uses_dynamic_stack: false
    .vgpr_count:     251
    .vgpr_spill_count: 0
    .wavefront_size: 64
